# attention loop: first PV group's transposed V reads issued inside QK^T (after its 12th MFMA) so their LDS latency is covered
# speedup vs baseline: 1.0188x; 1.0006x over previous
.LBB0_433:
	ds_read_b128 v[64:67], v166 offset:49152
	ds_read_b128 v[68:71], v166 offset:57344
	ds_read_b128 v[176:179], v167 offset:49152
	ds_read_b128 v[198:201], v167 offset:57344
	ds_read_b128 v[202:205], v168 offset:49152
	ds_read_b128 v[210:213], v168 offset:57344
	s_add_u32 m0, s86, 0x8000
	s_nop 0
	global_load_lds_dwordx4 v247, s[82:83]
	s_add_u32 m0, s86, 0x8400
	s_nop 0
	global_load_lds_dwordx4 v248, s[82:83]
	s_add_u32 s82, s82, 0x8000
	s_addc_u32 s83, s83, 0
	v_exp_f32_e32 v142, v142
	v_exp_f32_e32 v143, v143
	s_waitcnt lgkmcnt(5)
	v_mfma_f32_32x32x16_bf16 v[80:95], v[64:67], v[124:127], 0
	v_exp_f32_e32 v180, v140
	v_exp_f32_e32 v181, v141
	v_exp_f32_e32 v206, v138
	v_exp_f32_e32 v207, v135
	v_exp_f32_e32 v148, v148
	v_exp_f32_e32 v149, v149
	v_exp_f32_e32 v209, v146
	s_waitcnt lgkmcnt(4)
	v_mfma_f32_32x32x16_bf16 v[64:79], v[68:71], v[124:127], 0
	v_cvt_pk_bf16_f32 v135, v192, v193
	v_cvt_pk_bf16_f32 v138, v182, v183
	v_cvt_pk_bf16_f32 v140, v185, v187
	v_cvt_pk_bf16_f32 v141, v188, v189
	s_nop 0
	s_waitcnt lgkmcnt(3)
	v_mfma_f32_32x32x16_bf16 v[80:95], v[176:179], v[120:123], v[80:95]
	ds_read_b128 v[176:179], v169 offset:49152
	ds_read_b128 v[214:217], v169 offset:57344
	ds_read_b128 v[218:221], v170 offset:49152
	ds_read_b128 v[222:225], v170 offset:57344
	ds_read_b128 v[226:229], v171 offset:49152
	ds_read_b128 v[230:233], v171 offset:57344
	ds_read_b128 v[234:237], v172 offset:49152
	ds_read_b128 v[238:241], v172 offset:57344
	s_waitcnt lgkmcnt(10)
	v_mfma_f32_32x32x16_bf16 v[64:79], v[198:201], v[120:123], v[64:79]
	ds_read_b128 v[198:201], v173 offset:49152
	ds_read_b128 v[242:245], v173 offset:57344
	s_waitcnt lgkmcnt(11)
	v_mfma_f32_32x32x16_bf16 v[80:95], v[202:205], v[112:115], v[80:95]
	v_exp_f32_e32 v205, v134
	v_add_f32_e32 v134, v191, v190
	v_add_f32_e32 v134, v192, v134
	v_add_f32_e32 v134, v193, v134
	v_add_f32_e32 v134, v194, v134
	v_add_f32_e32 v134, v196, v134
	s_waitcnt lgkmcnt(10)
	v_mfma_f32_32x32x16_bf16 v[64:79], v[210:213], v[112:115], v[64:79]
	v_add_f32_e32 v134, v195, v134
	v_add_f32_e32 v134, v197, v134
	v_add_f32_e32 v134, v182, v134
	v_add_f32_e32 v134, v183, v134
	v_add_f32_e32 v134, v184, v134
	v_add_f32_e32 v134, v186, v134
	v_add_f32_e32 v134, v185, v134
	s_waitcnt lgkmcnt(9)
	v_mfma_f32_32x32x16_bf16 v[80:95], v[176:179], v[116:119], v[80:95]
	v_add_f32_e32 v134, v187, v134
	v_add_f32_e32 v134, v188, v134
	v_add_f32_e32 v134, v189, v134
	v_add_f32_e32 v134, v142, v134
	v_exp_f32_e32 v202, v139
	v_add_f32_e32 v134, v143, v134
	v_exp_f32_e32 v203, v136
	s_waitcnt lgkmcnt(8)
	v_mfma_f32_32x32x16_bf16 v[64:79], v[214:217], v[116:119], v[64:79]
	v_add_f32_e32 v134, v180, v134
	v_exp_f32_e32 v204, v137
	v_add_f32_e32 v134, v181, v134
	v_add_f32_e32 v134, v206, v134
	v_add_f32_e32 v134, v202, v134
	v_add_f32_e32 v134, v203, v134
	v_add_f32_e32 v134, v204, v134
	s_waitcnt lgkmcnt(7)
	v_mfma_f32_32x32x16_bf16 v[80:95], v[218:221], v[108:111], v[80:95]
	v_add_f32_e32 v134, v205, v134
	v_exp_f32_e32 v210, v147
	v_add_f32_e32 v134, v207, v134
	v_exp_f32_e32 v211, v144
	v_add_f32_e32 v134, v148, v134
	v_exp_f32_e32 v212, v145
	v_add_f32_e32 v134, v149, v134
	s_waitcnt lgkmcnt(6)
	v_mfma_f32_32x32x16_bf16 v[64:79], v[222:225], v[108:111], v[64:79]
	v_add_f32_e32 v134, v209, v134
	v_add_f32_e32 v134, v210, v134
	v_add_f32_e32 v134, v211, v134
	v_add_f32_e32 v176, v212, v134
	v_cvt_pk_bf16_f32 v134, v190, v191
	v_cvt_pk_bf16_f32 v136, v194, v196
	s_waitcnt lgkmcnt(5)
	v_mfma_f32_32x32x16_bf16 v[80:95], v[226:229], v[104:107], v[80:95]
	v_cvt_pk_bf16_f32 v137, v195, v197
	v_cvt_pk_bf16_f32 v139, v184, v186
	v_cvt_pk_bf16_f32 v142, v142, v143
	s_waitcnt lgkmcnt(4)
	v_mfma_f32_32x32x16_bf16 v[64:79], v[230:233], v[104:107], v[64:79]
	ds_read_b64_tr_b16 v[218:219], v161 offset:0
	ds_read_b64_tr_b16 v[220:221], v161 offset:2048
	ds_read_b64_tr_b16 v[222:223], v161 offset:4096
	ds_read_b64_tr_b16 v[224:225], v161 offset:6144
	ds_read_b64_tr_b16 v[226:227], v161 offset:8192
	ds_read_b64_tr_b16 v[228:229], v161 offset:10240
	ds_read_b64_tr_b16 v[230:231], v161 offset:12288
	ds_read_b64_tr_b16 v[232:233], v161 offset:14336
	v_cvt_pk_bf16_f32 v143, v180, v181
	v_cvt_pk_bf16_f32 v144, v206, v202
	v_cvt_pk_bf16_f32 v145, v203, v204
	v_cvt_pk_bf16_f32 v146, v205, v207
	v_cvt_pk_bf16_f32 v147, v148, v149
	v_cvt_pk_bf16_f32 v148, v209, v210
	v_cvt_pk_bf16_f32 v149, v211, v212
	s_waitcnt lgkmcnt(11)
	v_mfma_f32_32x32x16_bf16 v[80:95], v[234:237], v[100:103], v[80:95]
	s_waitcnt lgkmcnt(10)
	v_mfma_f32_32x32x16_bf16 v[64:79], v[238:241], v[100:103], v[64:79]
	s_waitcnt lgkmcnt(9)
	v_mfma_f32_32x32x16_bf16 v[80:95], v[198:201], v[96:99], v[80:95]
	s_waitcnt lgkmcnt(8)
	v_mfma_f32_32x32x16_bf16 v[64:79], v[242:245], v[96:99], v[64:79]
	s_waitcnt lgkmcnt(0)
	s_nop 0
	v_mfma_f32_32x32x16_bf16 v[0:15], v[134:137], v[218:221], v[0:15]
	ds_read_b64_tr_b16 v[196:197], v161 offset:0x200
	ds_read_b64_tr_b16 v[198:199], v161 offset:0xa00
	v_max_f32_e32 v234, v80, v81
	v_max3_f32 v234, v234, v82, v83
	v_max3_f32 v234, v234, v84, v85
	v_max3_f32 v234, v234, v86, v87
	v_max3_f32 v234, v234, v88, v89
	v_mfma_f32_32x32x16_bf16 v[0:15], v[138:141], v[222:225], v[0:15]
	ds_read_b64_tr_b16 v[200:201], v161 offset:0x1200
	ds_read_b64_tr_b16 v[202:203], v161 offset:0x1a00
	v_max3_f32 v234, v234, v90, v91
	v_max3_f32 v234, v234, v92, v93
	v_max3_f32 v234, v234, v94, v95
	v_max3_f32 v234, v234, v64, v65
	v_max3_f32 v234, v234, v66, v67
	v_mfma_f32_32x32x16_bf16 v[0:15], v[142:145], v[226:229], v[0:15]
	ds_read_b64_tr_b16 v[204:205], v161 offset:0x2200
	ds_read_b64_tr_b16 v[206:207], v161 offset:0x2a00
	ds_read_b64_tr_b16 v[214:215], v161 offset:0x3200
	ds_read_b64_tr_b16 v[216:217], v161 offset:0x3a00
	v_max3_f32 v234, v234, v68, v69
	v_max3_f32 v234, v234, v70, v71
	v_max3_f32 v234, v234, v72, v73
	v_max3_f32 v234, v234, v74, v75
	v_max3_f32 v234, v234, v76, v77
	s_waitcnt lgkmcnt(0)
	v_mfma_f32_32x32x16_bf16 v[0:15], v[146:149], v[230:233], v[0:15]
	v_max3_f32 v234, v234, v78, v79
	v_mov_b32_e32 v235, v234
	v_mfma_f32_32x32x16_bf16 v[48:63], v[134:137], v[196:199], v[48:63]
	ds_read_b64_tr_b16 v[196:197], v161 offset:0x400
	ds_read_b64_tr_b16 v[198:199], v161 offset:0xc00
	v_permlane32_swap_b32_e32 v234, v235
	v_max_f32_e32 v234, v234, v235
	v_mfma_f32_32x32x16_bf16 v[48:63], v[138:141], v[200:203], v[48:63]
	ds_read_b64_tr_b16 v[200:201], v161 offset:0x1400
	ds_read_b64_tr_b16 v[202:203], v161 offset:0x1c00
	v_sub_f32_e32 v235, v234, v175
	v_max_f32_e32 v234, v175, v234
	v_sub_f32_e32 v236, v175, v234
	v_mul_f32_e32 v236, 0x3e0293ee, v236
	v_mfma_f32_32x32x16_bf16 v[48:63], v[142:145], v[204:207], v[48:63]
	ds_read_b64_tr_b16 v[204:205], v161 offset:0x2400
	ds_read_b64_tr_b16 v[206:207], v161 offset:0x2c00
	ds_read_b64_tr_b16 v[210:211], v161 offset:0x3400
	ds_read_b64_tr_b16 v[212:213], v161 offset:0x3c00
	v_exp_f32_e32 v236, v236
	v_cmp_ge_f32_e32 vcc, s15, v235
	s_cmp_eq_u64 vcc, exec
	s_cselect_b64 s[8:9], -1, 0
	s_waitcnt lgkmcnt(0)
	v_mfma_f32_32x32x16_bf16 v[48:63], v[146:149], v[214:217], v[48:63]
	v_cndmask_b32_e64 v179, v236, 1.0, s[8:9]
	v_cndmask_b32_e64 v234, v234, v175, s[8:9]
	v_mul_f32_e32 v238, 0xbe0293ee, v234
	v_fmamk_f32 v88, v88, 0x3e0293ee, v238
	v_fmamk_f32 v89, v89, 0x3e0293ee, v238
	v_fmamk_f32 v80, v80, 0x3e0293ee, v238
	v_fmamk_f32 v81, v81, 0x3e0293ee, v238
	v_mfma_f32_32x32x16_bf16 v[32:47], v[134:137], v[196:199], v[32:47]
	ds_read_b64_tr_b16 v[196:197], v161 offset:0x600
	ds_read_b64_tr_b16 v[198:199], v161 offset:0xe00
	v_fmamk_f32 v82, v82, 0x3e0293ee, v238
	v_fmamk_f32 v83, v83, 0x3e0293ee, v238
	v_fmamk_f32 v84, v84, 0x3e0293ee, v238
	v_fmamk_f32 v85, v85, 0x3e0293ee, v238
	v_fmamk_f32 v86, v86, 0x3e0293ee, v238
	v_fmamk_f32 v87, v87, 0x3e0293ee, v238
	v_fmamk_f32 v90, v90, 0x3e0293ee, v238
	v_fmamk_f32 v91, v91, 0x3e0293ee, v238
	v_mfma_f32_32x32x16_bf16 v[32:47], v[138:141], v[200:203], v[32:47]
	ds_read_b64_tr_b16 v[200:201], v161 offset:0x1600
	ds_read_b64_tr_b16 v[202:203], v161 offset:0x1e00
	v_fmamk_f32 v92, v92, 0x3e0293ee, v238
	v_fmamk_f32 v93, v93, 0x3e0293ee, v238
	v_fmamk_f32 v94, v94, 0x3e0293ee, v238
	v_fmamk_f32 v95, v95, 0x3e0293ee, v238
	v_fmamk_f32 v188, v64, 0x3e0293ee, v238
	v_fmamk_f32 v189, v65, 0x3e0293ee, v238
	v_fmamk_f32 v190, v66, 0x3e0293ee, v238
	v_fmamk_f32 v191, v67, 0x3e0293ee, v238
	v_mfma_f32_32x32x16_bf16 v[32:47], v[142:145], v[204:207], v[32:47]
	ds_read_b64_tr_b16 v[204:205], v161 offset:0x2600
	ds_read_b64_tr_b16 v[206:207], v161 offset:0x2e00
	ds_read_b64_tr_b16 v[214:215], v161 offset:0x3600
	ds_read_b64_tr_b16 v[216:217], v161 offset:0x3e00
	v_fmamk_f32 v182, v70, 0x3e0293ee, v238
	v_fmamk_f32 v183, v71, 0x3e0293ee, v238
	v_fmamk_f32 v184, v72, 0x3e0293ee, v238
	v_fmamk_f32 v185, v73, 0x3e0293ee, v238
	v_fmamk_f32 v186, v74, 0x3e0293ee, v238
	v_fmamk_f32 v187, v75, 0x3e0293ee, v238
	s_waitcnt lgkmcnt(0)
	v_mfma_f32_32x32x16_bf16 v[32:47], v[146:149], v[210:213], v[32:47]
	v_fmamk_f32 v192, v68, 0x3e0293ee, v238
	v_fmamk_f32 v181, v69, 0x3e0293ee, v238
	v_fmamk_f32 v180, v76, 0x3e0293ee, v238
	v_mfma_f32_32x32x16_bf16 v[16:31], v[134:137], v[196:199], v[16:31]
	v_fmamk_f32 v193, v77, 0x3e0293ee, v238
	v_fmamk_f32 v194, v78, 0x3e0293ee, v238
	v_fmamk_f32 v177, v79, 0x3e0293ee, v238
	v_mov_b32_e32 v134, v234
	v_exp_f32_e32 v135, v88
	v_exp_f32_e32 v136, v89
	v_exp_f32_e32 v137, v90
	v_mfma_f32_32x32x16_bf16 v[16:31], v[138:141], v[200:203], v[16:31]
	v_exp_f32_e32 v139, v91
	v_exp_f32_e32 v138, v92
	v_exp_f32_e32 v140, v93
	v_exp_f32_e32 v141, v94
	v_mfma_f32_32x32x16_bf16 v[16:31], v[142:145], v[204:207], v[16:31]
	v_exp_f32_e32 v142, v95
	v_exp_f32_e32 v143, v80
	v_exp_f32_e32 v144, v81
	v_exp_f32_e32 v145, v82
	v_mfma_f32_32x32x16_bf16 v[16:31], v[146:149], v[214:217], v[16:31]
	v_exp_f32_e32 v146, v83
	v_exp_f32_e32 v147, v84
	v_exp_f32_e32 v149, v85
	v_exp_f32_e32 v148, v86
	v_exp_f32_e32 v175, v87
	v_cmp_gt_f32_e32 vcc, 1.0, v179
	s_waitcnt vmcnt(0)
	s_barrier
	s_cbranch_vccz .LBB0_437
	s_and_saveexec_b64 s[2:3], s[6:7]
	ds_write_b32 v158, v179 offset:128
	s_or_b64 exec, exec, s[2:3]
	s_waitcnt lgkmcnt(0)
	v_add_u32_e32 v234, v131, v128
	ds_read_b128 v[218:221], v234 offset:224
	ds_read_b128 v[222:225], v234 offset:192
	ds_read_b128 v[226:229], v234 offset:160
	ds_read_b128 v[230:233], v234 offset:128
	s_waitcnt lgkmcnt(3)
	v_pk_mul_f32 v[12:13], v[12:13], v[218:219]
	s_waitcnt lgkmcnt(2)
	v_pk_mul_f32 v[8:9], v[8:9], v[222:223]
	s_waitcnt lgkmcnt(1)
	v_pk_mul_f32 v[4:5], v[4:5], v[226:227]
	v_pk_mul_f32 v[14:15], v[14:15], v[220:221]
	v_pk_mul_f32 v[10:11], v[10:11], v[224:225]
	v_pk_mul_f32 v[6:7], v[6:7], v[228:229]
	s_waitcnt lgkmcnt(0)
	v_pk_mul_f32 v[2:3], v[2:3], v[232:233]
	v_pk_mul_f32 v[0:1], v[0:1], v[230:231]
	v_pk_mul_f32 v[60:61], v[60:61], v[218:219]
	v_pk_mul_f32 v[56:57], v[56:57], v[222:223]
	v_pk_mul_f32 v[52:53], v[52:53], v[226:227]
	v_pk_mul_f32 v[62:63], v[62:63], v[220:221]
	v_pk_mul_f32 v[58:59], v[58:59], v[224:225]
	v_pk_mul_f32 v[54:55], v[54:55], v[228:229]
	v_pk_mul_f32 v[50:51], v[50:51], v[232:233]
	v_pk_mul_f32 v[48:49], v[48:49], v[230:231]
	v_pk_mul_f32 v[44:45], v[44:45], v[218:219]
	v_pk_mul_f32 v[40:41], v[40:41], v[222:223]
	v_pk_mul_f32 v[36:37], v[36:37], v[226:227]
	v_pk_mul_f32 v[46:47], v[46:47], v[220:221]
	v_pk_mul_f32 v[42:43], v[42:43], v[224:225]
	v_pk_mul_f32 v[38:39], v[38:39], v[228:229]
	v_pk_mul_f32 v[34:35], v[34:35], v[232:233]
	v_pk_mul_f32 v[32:33], v[32:33], v[230:231]
	v_pk_mul_f32 v[28:29], v[28:29], v[218:219]
	v_pk_mul_f32 v[24:25], v[24:25], v[222:223]
	v_pk_mul_f32 v[20:21], v[20:21], v[226:227]
	v_pk_mul_f32 v[30:31], v[30:31], v[220:221]
	v_pk_mul_f32 v[26:27], v[26:27], v[224:225]
	v_pk_mul_f32 v[22:23], v[22:23], v[228:229]
	v_pk_mul_f32 v[18:19], v[18:19], v[232:233]
	v_pk_mul_f32 v[16:17], v[16:17], v[230:231]
.LBB0_437:
	ds_read_b128 v[64:67], v166 offset:32768
	ds_read_b128 v[68:71], v166 offset:40960
	ds_read_b128 v[196:199], v167 offset:32768
	ds_read_b128 v[200:203], v167 offset:40960
	ds_read_b128 v[204:207], v168 offset:32768
	ds_read_b128 v[210:213], v168 offset:40960
	s_add_u32 m0, s86, 0x0
	s_nop 0
	global_load_lds_dwordx4 v249, s[84:85]
	s_add_u32 m0, s86, 0x380
	s_nop 0
	global_load_lds_dwordx4 v249, s[84:85] offset:128
	s_add_u32 s84, s84, 0x8000
	s_addc_u32 s85, s85, 0
	s_add_u32 m0, s86, 0xc000
	s_nop 0
	global_load_lds_dwordx4 v247, s[82:83]
	s_add_u32 m0, s86, 0xc400
	s_nop 0
	global_load_lds_dwordx4 v248, s[82:83]
	s_add_u32 s82, s82, 0x8000
	s_addc_u32 s83, s83, 0
	v_exp_f32_e32 v188, v188
	v_exp_f32_e32 v189, v189
	s_waitcnt lgkmcnt(5)
	v_mfma_f32_32x32x16_bf16 v[80:95], v[64:67], v[124:127], 0
	v_exp_f32_e32 v190, v190
	v_exp_f32_e32 v191, v191
	v_exp_f32_e32 v192, v192
	v_exp_f32_e32 v195, v181
	v_exp_f32_e32 v182, v182
	v_exp_f32_e32 v183, v183
	v_exp_f32_e32 v184, v184
	s_waitcnt lgkmcnt(4)
	v_mfma_f32_32x32x16_bf16 v[64:79], v[68:71], v[124:127], 0
	v_exp_f32_e32 v185, v185
	v_exp_f32_e32 v186, v186
	v_exp_f32_e32 v187, v187
	v_exp_f32_e32 v193, v193
	v_exp_f32_e32 v194, v194
	v_exp_f32_e32 v177, v177
	s_waitcnt lgkmcnt(3)
	v_mfma_f32_32x32x16_bf16 v[80:95], v[196:199], v[120:123], v[80:95]
	ds_read_b128 v[196:199], v169 offset:32768
	ds_read_b128 v[214:217], v169 offset:40960
	ds_read_b128 v[218:221], v170 offset:32768
	ds_read_b128 v[222:225], v170 offset:40960
	ds_read_b128 v[226:229], v171 offset:32768
	ds_read_b128 v[230:233], v171 offset:40960
	ds_read_b128 v[234:237], v172 offset:32768
	ds_read_b128 v[238:241], v172 offset:40960
	s_waitcnt lgkmcnt(10)
	v_mfma_f32_32x32x16_bf16 v[64:79], v[200:203], v[120:123], v[64:79]
	ds_read_b128 v[200:203], v173 offset:32768
	ds_read_b128 v[242:245], v173 offset:40960
	s_waitcnt lgkmcnt(11)
	v_mfma_f32_32x32x16_bf16 v[80:95], v[204:207], v[112:115], v[80:95]
	v_exp_f32_e32 v204, v180
	v_add_f32_e32 v180, v144, v143
	v_add_f32_e32 v180, v145, v180
	v_add_f32_e32 v180, v146, v180
	v_add_f32_e32 v180, v147, v180
	v_add_f32_e32 v180, v149, v180
	s_waitcnt lgkmcnt(10)
	v_mfma_f32_32x32x16_bf16 v[64:79], v[210:213], v[112:115], v[64:79]
	v_add_f32_e32 v180, v148, v180
	v_add_f32_e32 v180, v175, v180
	v_add_f32_e32 v180, v135, v180
	v_add_f32_e32 v180, v136, v180
	v_add_f32_e32 v180, v137, v180
	v_add_f32_e32 v180, v139, v180
	v_add_f32_e32 v180, v138, v180
	s_waitcnt lgkmcnt(9)
	v_mfma_f32_32x32x16_bf16 v[80:95], v[196:199], v[116:119], v[80:95]
	v_add_f32_e32 v180, v140, v180
	v_add_f32_e32 v180, v141, v180
	v_add_f32_e32 v180, v142, v180
	v_add_f32_e32 v180, v188, v180
	v_add_f32_e32 v180, v189, v180
	v_add_f32_e32 v180, v190, v180
	v_add_f32_e32 v180, v191, v180
	s_waitcnt lgkmcnt(8)
	v_mfma_f32_32x32x16_bf16 v[64:79], v[214:217], v[116:119], v[64:79]
	v_add_f32_e32 v180, v192, v180
	v_add_f32_e32 v180, v195, v180
	v_add_f32_e32 v180, v182, v180
	v_add_f32_e32 v180, v183, v180
	v_add_f32_e32 v180, v184, v180
	v_add_f32_e32 v180, v185, v180
	v_add_f32_e32 v180, v186, v180
	s_waitcnt lgkmcnt(7)
	v_mfma_f32_32x32x16_bf16 v[80:95], v[218:221], v[108:111], v[80:95]
	v_add_f32_e32 v180, v187, v180
	v_add_f32_e32 v180, v204, v180
	v_add_f32_e32 v180, v193, v180
	v_add_f32_e32 v180, v194, v180
	v_add_f32_e32 v180, v177, v180
	s_waitcnt lgkmcnt(6)
	v_mfma_f32_32x32x16_bf16 v[64:79], v[222:225], v[108:111], v[64:79]
	v_cvt_pk_bf16_f32 v144, v143, v144
	v_cvt_pk_bf16_f32 v145, v145, v146
	v_cvt_pk_bf16_f32 v146, v147, v149
	v_cvt_pk_bf16_f32 v147, v148, v175
	v_cvt_pk_bf16_f32 v136, v135, v136
	v_cvt_pk_bf16_f32 v137, v137, v139
	v_cvt_pk_bf16_f32 v138, v138, v140
	s_waitcnt lgkmcnt(5)
	v_mfma_f32_32x32x16_bf16 v[80:95], v[226:229], v[104:107], v[80:95]
	v_cvt_pk_bf16_f32 v139, v141, v142
	v_cvt_pk_bf16_f32 v140, v188, v189
	v_cvt_pk_bf16_f32 v141, v190, v191
	v_cvt_pk_bf16_f32 v142, v192, v195
	v_cvt_pk_bf16_f32 v143, v182, v183
	v_cvt_pk_bf16_f32 v182, v184, v185
	v_cvt_pk_bf16_f32 v183, v186, v187
	s_waitcnt lgkmcnt(4)
	v_mfma_f32_32x32x16_bf16 v[64:79], v[230:233], v[104:107], v[64:79]
	ds_read_b64_tr_b16 v[218:219], v160 offset:0
	ds_read_b64_tr_b16 v[220:221], v160 offset:2048
	ds_read_b64_tr_b16 v[222:223], v160 offset:4096
	ds_read_b64_tr_b16 v[224:225], v160 offset:6144
	ds_read_b64_tr_b16 v[226:227], v160 offset:8192
	ds_read_b64_tr_b16 v[228:229], v160 offset:10240
	ds_read_b64_tr_b16 v[230:231], v160 offset:12288
	ds_read_b64_tr_b16 v[232:233], v160 offset:14336
	v_cvt_pk_bf16_f32 v184, v204, v193
	v_cvt_pk_bf16_f32 v185, v194, v177
	s_waitcnt lgkmcnt(11)
	v_mfma_f32_32x32x16_bf16 v[80:95], v[234:237], v[100:103], v[80:95]
	s_waitcnt lgkmcnt(10)
	v_mfma_f32_32x32x16_bf16 v[64:79], v[238:241], v[100:103], v[64:79]
	s_waitcnt lgkmcnt(9)
	v_mfma_f32_32x32x16_bf16 v[80:95], v[200:203], v[96:99], v[80:95]
	s_waitcnt lgkmcnt(8)
	v_mfma_f32_32x32x16_bf16 v[64:79], v[242:245], v[96:99], v[64:79]
	s_waitcnt lgkmcnt(0)
	s_nop 0
	v_mfma_f32_32x32x16_bf16 v[0:15], v[144:147], v[218:221], v[0:15]
	ds_read_b64_tr_b16 v[202:203], v160 offset:0x200
	ds_read_b64_tr_b16 v[204:205], v160 offset:0xa00
	v_max_f32_e32 v242, v80, v81
	v_max3_f32 v242, v242, v82, v83
	v_max3_f32 v242, v242, v84, v85
	v_max3_f32 v242, v242, v86, v87
	v_max3_f32 v242, v242, v88, v89
	v_mfma_f32_32x32x16_bf16 v[0:15], v[136:139], v[222:225], v[0:15]
	ds_read_b64_tr_b16 v[210:211], v160 offset:0x1200
	ds_read_b64_tr_b16 v[212:213], v160 offset:0x1a00
	v_max3_f32 v242, v242, v90, v91
	v_max3_f32 v242, v242, v92, v93
	v_max3_f32 v242, v242, v94, v95
	v_max3_f32 v242, v242, v64, v65
	v_max3_f32 v242, v242, v66, v67
	v_mfma_f32_32x32x16_bf16 v[0:15], v[140:143], v[226:229], v[0:15]
	ds_read_b64_tr_b16 v[214:215], v160 offset:0x2200
	ds_read_b64_tr_b16 v[216:217], v160 offset:0x2a00
	ds_read_b64_tr_b16 v[222:223], v160 offset:0x3200
	ds_read_b64_tr_b16 v[224:225], v160 offset:0x3a00
	v_max3_f32 v242, v242, v68, v69
	v_max3_f32 v242, v242, v70, v71
	v_max3_f32 v242, v242, v72, v73
	v_max3_f32 v242, v242, v74, v75
	v_max3_f32 v242, v242, v76, v77
	s_waitcnt lgkmcnt(0)
	v_mfma_f32_32x32x16_bf16 v[0:15], v[182:185], v[230:233], v[0:15]
	v_max3_f32 v242, v242, v78, v79
	v_mov_b32_e32 v243, v242
	v_mfma_f32_32x32x16_bf16 v[48:63], v[144:147], v[202:205], v[48:63]
	ds_read_b64_tr_b16 v[202:203], v160 offset:0x400
	ds_read_b64_tr_b16 v[204:205], v160 offset:0xc00
	v_permlane32_swap_b32_e32 v242, v243
	v_max_f32_e32 v242, v242, v243
	v_mfma_f32_32x32x16_bf16 v[48:63], v[136:139], v[210:213], v[48:63]
	ds_read_b64_tr_b16 v[210:211], v160 offset:0x1400
	ds_read_b64_tr_b16 v[212:213], v160 offset:0x1c00
	v_sub_f32_e32 v243, v242, v134
	v_max_f32_e32 v242, v134, v242
	v_sub_f32_e32 v148, v134, v242
	v_mul_f32_e32 v148, 0x3e0293ee, v148
	v_mfma_f32_32x32x16_bf16 v[48:63], v[140:143], v[214:217], v[48:63]
	ds_read_b64_tr_b16 v[214:215], v160 offset:0x2400
	ds_read_b64_tr_b16 v[216:217], v160 offset:0x2c00
	ds_read_b64_tr_b16 v[218:219], v160 offset:0x3400
	ds_read_b64_tr_b16 v[220:221], v160 offset:0x3c00
	v_exp_f32_e32 v148, v148
	v_cmp_ge_f32_e32 vcc, s15, v243
	s_cmp_eq_u64 vcc, exec
	s_cselect_b64 s[8:9], -1, 0
	s_waitcnt lgkmcnt(0)
	v_mfma_f32_32x32x16_bf16 v[48:63], v[182:185], v[222:225], v[48:63]
	v_cndmask_b32_e64 v177, v148, 1.0, s[8:9]
	v_cndmask_b32_e64 v175, v242, v134, s[8:9]
	v_mul_f32_e32 v244, 0xbe0293ee, v175
	v_fmamk_f32 v80, v80, 0x3e0293ee, v244
	v_fmamk_f32 v81, v81, 0x3e0293ee, v244
	v_fmamk_f32 v82, v82, 0x3e0293ee, v244
	v_fmamk_f32 v83, v83, 0x3e0293ee, v244
	v_mfma_f32_32x32x16_bf16 v[32:47], v[144:147], v[202:205], v[32:47]
	ds_read_b64_tr_b16 v[202:203], v160 offset:0x600
	ds_read_b64_tr_b16 v[204:205], v160 offset:0xe00
	v_fmamk_f32 v84, v84, 0x3e0293ee, v244
	v_fmamk_f32 v85, v85, 0x3e0293ee, v244
	v_fmamk_f32 v86, v86, 0x3e0293ee, v244
	v_fmamk_f32 v87, v87, 0x3e0293ee, v244
	v_fmamk_f32 v88, v88, 0x3e0293ee, v244
	v_fmamk_f32 v89, v89, 0x3e0293ee, v244
	v_fmamk_f32 v90, v90, 0x3e0293ee, v244
	v_fmamk_f32 v91, v91, 0x3e0293ee, v244
	v_mfma_f32_32x32x16_bf16 v[32:47], v[136:139], v[210:213], v[32:47]
	ds_read_b64_tr_b16 v[210:211], v160 offset:0x1600
	ds_read_b64_tr_b16 v[212:213], v160 offset:0x1e00
	v_fmamk_f32 v92, v92, 0x3e0293ee, v244
	v_fmamk_f32 v93, v93, 0x3e0293ee, v244
	v_fmamk_f32 v94, v94, 0x3e0293ee, v244
	v_fmamk_f32 v95, v95, 0x3e0293ee, v244
	v_fmamk_f32 v134, v72, 0x3e0293ee, v244
	v_fmamk_f32 v135, v73, 0x3e0293ee, v244
	v_fmamk_f32 v148, v74, 0x3e0293ee, v244
	v_fmamk_f32 v149, v75, 0x3e0293ee, v244
	v_mfma_f32_32x32x16_bf16 v[32:47], v[140:143], v[214:217], v[32:47]
	ds_read_b64_tr_b16 v[214:215], v160 offset:0x2600
	ds_read_b64_tr_b16 v[216:217], v160 offset:0x2e00
	ds_read_b64_tr_b16 v[222:223], v160 offset:0x3600
	ds_read_b64_tr_b16 v[224:225], v160 offset:0x3e00
	v_exp_f32_e32 v190, v80
	v_exp_f32_e32 v191, v81
	v_exp_f32_e32 v192, v82
	s_waitcnt lgkmcnt(0)
	v_mfma_f32_32x32x16_bf16 v[32:47], v[182:185], v[218:221], v[32:47]
	v_exp_f32_e32 v193, v83
	v_exp_f32_e32 v194, v84
	v_exp_f32_e32 v196, v85
	v_mfma_f32_32x32x16_bf16 v[16:31], v[144:147], v[202:205], v[16:31]
	v_fmamk_f32 v144, v78, 0x3e0293ee, v244
	v_fmamk_f32 v145, v79, 0x3e0293ee, v244
	v_fmamk_f32 v146, v76, 0x3e0293ee, v244
	v_fmamk_f32 v147, v77, 0x3e0293ee, v244
	v_exp_f32_e32 v195, v86
	v_exp_f32_e32 v197, v87
	v_mfma_f32_32x32x16_bf16 v[16:31], v[136:139], v[210:213], v[16:31]
	v_fmamk_f32 v136, v70, 0x3e0293ee, v244
	v_fmamk_f32 v137, v71, 0x3e0293ee, v244
	v_fmamk_f32 v138, v68, 0x3e0293ee, v244
	v_fmamk_f32 v139, v69, 0x3e0293ee, v244
	v_exp_f32_e32 v186, v91
	v_exp_f32_e32 v187, v93
	v_mfma_f32_32x32x16_bf16 v[16:31], v[140:143], v[214:217], v[16:31]
	v_fmamk_f32 v140, v66, 0x3e0293ee, v244
	v_fmamk_f32 v141, v67, 0x3e0293ee, v244
	v_fmamk_f32 v142, v64, 0x3e0293ee, v244
	v_fmamk_f32 v143, v65, 0x3e0293ee, v244
	v_exp_f32_e32 v188, v94
	v_exp_f32_e32 v189, v95
	v_mfma_f32_32x32x16_bf16 v[16:31], v[182:185], v[222:225], v[16:31]
	v_exp_f32_e32 v182, v88
	v_exp_f32_e32 v183, v89
	v_exp_f32_e32 v184, v90
	v_exp_f32_e32 v185, v92
	v_cmp_gt_f32_e32 vcc, 1.0, v177
	s_waitcnt vmcnt(0)
	s_barrier
	s_add_u32 m0, s86, 0x4000
	s_nop 0
	global_load_lds_dwordx4 v249, s[84:85]
	s_add_u32 m0, s86, 0x4380
	s_nop 0
	global_load_lds_dwordx4 v249, s[84:85] offset:128
	s_add_u32 s84, s84, 0x8000
	s_addc_u32 s85, s85, 0
	s_cbranch_vccz .LBB0_441
	s_and_saveexec_b64 s[2:3], s[6:7]
	ds_write_b32 v158, v177 offset:128
	s_or_b64 exec, exec, s[2:3]
	s_waitcnt lgkmcnt(0)
	v_add_u32_e32 v242, v131, v128
	ds_read_b128 v[226:229], v242 offset:224
	ds_read_b128 v[230:233], v242 offset:192
	ds_read_b128 v[234:237], v242 offset:160
	ds_read_b128 v[238:241], v242 offset:128
	s_waitcnt lgkmcnt(3)
	v_pk_mul_f32 v[12:13], v[12:13], v[226:227]
	s_waitcnt lgkmcnt(2)
	v_pk_mul_f32 v[8:9], v[8:9], v[230:231]
	s_waitcnt lgkmcnt(1)
	v_pk_mul_f32 v[4:5], v[4:5], v[234:235]
	v_pk_mul_f32 v[14:15], v[14:15], v[228:229]
	v_pk_mul_f32 v[10:11], v[10:11], v[232:233]
	v_pk_mul_f32 v[6:7], v[6:7], v[236:237]
	s_waitcnt lgkmcnt(0)
	v_pk_mul_f32 v[2:3], v[2:3], v[240:241]
	v_pk_mul_f32 v[0:1], v[0:1], v[238:239]
	v_pk_mul_f32 v[60:61], v[60:61], v[226:227]
	v_pk_mul_f32 v[56:57], v[56:57], v[230:231]
	v_pk_mul_f32 v[52:53], v[52:53], v[234:235]
	v_pk_mul_f32 v[62:63], v[62:63], v[228:229]
	v_pk_mul_f32 v[58:59], v[58:59], v[232:233]
	v_pk_mul_f32 v[54:55], v[54:55], v[236:237]
	v_pk_mul_f32 v[50:51], v[50:51], v[240:241]
	v_pk_mul_f32 v[48:49], v[48:49], v[238:239]
	v_pk_mul_f32 v[44:45], v[44:45], v[226:227]
	v_pk_mul_f32 v[40:41], v[40:41], v[230:231]
	v_pk_mul_f32 v[36:37], v[36:37], v[234:235]
	v_pk_mul_f32 v[46:47], v[46:47], v[228:229]
	v_pk_mul_f32 v[42:43], v[42:43], v[232:233]
	v_pk_mul_f32 v[38:39], v[38:39], v[236:237]
	v_pk_mul_f32 v[34:35], v[34:35], v[240:241]
	v_pk_mul_f32 v[32:33], v[32:33], v[238:239]
	v_pk_mul_f32 v[28:29], v[28:29], v[226:227]
	v_pk_mul_f32 v[24:25], v[24:25], v[230:231]
	v_pk_mul_f32 v[20:21], v[20:21], v[234:235]
	v_pk_mul_f32 v[30:31], v[30:31], v[228:229]
	v_pk_mul_f32 v[26:27], v[26:27], v[232:233]
	v_pk_mul_f32 v[22:23], v[22:23], v[236:237]
	v_pk_mul_f32 v[18:19], v[18:19], v[240:241]
	v_pk_mul_f32 v[16:17], v[16:17], v[238:239]
